# attention: L2 warm-up touch loads in each unit's final step for the next unit's Q rows and the map-1 epilogue's GA / parked-O rows
# speedup vs baseline: 1.0022x; 1.0022x over previous
.LBB0_688:
	v_mbcnt_lo_u32_b32 v212, -1, 0
	v_mbcnt_hi_u32_b32 v212, -1, v212
	v_lshrrev_b32_e32 v213, 5, v212
	v_and_b32_e32 v212, 31, v212
	s_lshr_b32 s52, s75, 1
	s_sub_i32 s54, 15, s61
	s_bitcmp1_b32 s52, 0
	s_cselect_b32 s54, s54, s61
	s_and_b32 s55, s52, 2
	s_lshl_b32 s55, s55, 3
	s_add_i32 s54, s54, s55
	s_lshl_b32 s54, s54, 8
	s_lshr_b32 s55, s60, 3
	s_lshl_b32 s55, s55, 13
	s_add_i32 s54, s54, s55
	s_lshr_b32 s55, s85, 1
	s_add_i32 s54, s54, s55
	s_and_b32 s57, s60, 7
	s_bitcmp1_b32 s75, 0
	s_cbranch_scc0 .Lmy_t_q
	s_lshl_b32 s56, s54, 11
	s_lshl_b32 s53, s57, 8
	s_add_u32 s56, s56, s53
	s_add_u32 s56, s56, 0xe800000
	s_add_u32 s58, s22, s56
	s_addc_u32 s59, s23, 0
	v_lshlrev_b32_e32 v254, 11, v212
	v_lshl_or_b32 v254, v213, 7, v254
	global_load_dword v255, v254, s[58:59]
	s_lshl_b32 s56, s54, 12
	s_add_u32 s56, s56, s53
	s_add_u32 s58, s6, s56
	s_addc_u32 s59, s7, 0
	v_lshlrev_b32_e32 v254, 12, v212
	v_lshl_or_b32 v254, v213, 7, v254
	global_load_dword v255, v254, s[58:59]
.Lmy_t_q:
	s_add_i32 s52, s75, 1
	s_cmp_ge_u32 s52, 8
	s_cbranch_scc1 .Lmy_t_done
	s_and_b32 s53, s52, 1
	s_lshr_b32 s52, s52, 1
	s_sub_i32 s54, 15, s61
	s_bitcmp1_b32 s52, 0
	s_cselect_b32 s54, s54, s61
	s_and_b32 s55, s52, 2
	s_lshl_b32 s55, s55, 3
	s_add_i32 s54, s54, s55
	s_lshl_b32 s54, s54, 8
	s_lshr_b32 s55, s60, 3
	s_lshl_b32 s55, s55, 13
	s_add_i32 s54, s54, s55
	s_lshr_b32 s55, s85, 1
	s_add_i32 s54, s54, s55
	s_lshl_b32 s56, s54, 11
	s_lshl_b32 s55, s57, 1
	s_add_i32 s55, s55, s53
	s_lshl_b32 s55, s55, 7
	s_add_u32 s56, s56, s55
	s_add_u32 s56, s56, 0x2800000
	s_add_u32 s58, s22, s56
	s_addc_u32 s59, s23, 0
	v_lshlrev_b32_e32 v254, 11, v212
	v_lshl_or_b32 v254, v213, 6, v254
	global_load_dword v255, v254, s[58:59]

	.amdhsa_kernel _Z10hybrid_fwd4Args
		.amdhsa_group_segment_fixed_size 0
		.amdhsa_private_segment_fixed_size 0
		.amdhsa_kernarg_size 472
		.amdhsa_user_sgpr_count 2
		.amdhsa_user_sgpr_dispatch_ptr 0
		.amdhsa_user_sgpr_queue_ptr 0
		.amdhsa_user_sgpr_kernarg_segment_ptr 1
		.amdhsa_user_sgpr_dispatch_id 0
		.amdhsa_user_sgpr_kernarg_preload_length 0
		.amdhsa_user_sgpr_kernarg_preload_offset 0
		.amdhsa_user_sgpr_private_segment_size 0
		.amdhsa_uses_dynamic_stack 0
		.amdhsa_enable_private_segment 0
		.amdhsa_system_sgpr_workgroup_id_x 1
		.amdhsa_system_sgpr_workgroup_id_y 0
		.amdhsa_system_sgpr_workgroup_id_z 0
		.amdhsa_system_sgpr_workgroup_info 0
		.amdhsa_system_vgpr_workitem_id 2
		.amdhsa_next_free_vgpr 256
		.amdhsa_next_free_sgpr 102
		.amdhsa_accum_offset 256
		.amdhsa_reserve_vcc 1
		.amdhsa_float_round_mode_32 0
		.amdhsa_float_round_mode_16_64 0
		.amdhsa_float_denorm_mode_32 3
		.amdhsa_float_denorm_mode_16_64 3
		.amdhsa_dx10_clamp 1
		.amdhsa_ieee_mode 1
		.amdhsa_fp16_overflow 0
		.amdhsa_tg_split 0
		.amdhsa_exception_fp_ieee_invalid_op 0
		.amdhsa_exception_fp_denorm_src 0
		.amdhsa_exception_fp_ieee_div_zero 0
		.amdhsa_exception_fp_ieee_overflow 0
		.amdhsa_exception_fp_ieee_underflow 0
		.amdhsa_exception_fp_ieee_inexact 0
		.amdhsa_exception_int_div_zero 0
	.end_amdhsa_kernel

.Lfunc_end0:
	.size	_Z10hybrid_fwd4Args, .Lfunc_end0-_Z10hybrid_fwd4Args
	.set _Z10hybrid_fwd4Args.num_vgpr, 256
	.set _Z10hybrid_fwd4Args.num_agpr, 0
	.set _Z10hybrid_fwd4Args.numbered_sgpr, 102
	.set _Z10hybrid_fwd4Args.num_named_barrier, 0
	.set _Z10hybrid_fwd4Args.private_seg_size, 0
	.set _Z10hybrid_fwd4Args.uses_vcc, 1
	.set _Z10hybrid_fwd4Args.uses_flat_scratch, 0
	.set _Z10hybrid_fwd4Args.has_dyn_sized_stack, 0
	.set _Z10hybrid_fwd4Args.has_recursion, 0
	.set _Z10hybrid_fwd4Args.has_indirect_call, 0

amdhsa.kernels:
  - .agpr_count:     0
    .args:
      - .offset:         0
        .size:           216
        .value_kind:     by_value
      - .offset:         216
        .size:           4
        .value_kind:     hidden_block_count_x
      - .offset:         220
        .size:           4
        .value_kind:     hidden_block_count_y
      - .offset:         224
        .size:           4
        .value_kind:     hidden_block_count_z
      - .offset:         228
        .size:           2
        .value_kind:     hidden_group_size_x
      - .offset:         230
        .size:           2
        .value_kind:     hidden_group_size_y
      - .offset:         232
        .size:           2
        .value_kind:     hidden_group_size_z
      - .offset:         234
        .size:           2
        .value_kind:     hidden_remainder_x
      - .offset:         236
        .size:           2
        .value_kind:     hidden_remainder_y
      - .offset:         238
        .size:           2
        .value_kind:     hidden_remainder_z
      - .offset:         256
        .size:           8
        .value_kind:     hidden_global_offset_x
      - .offset:         264
        .size:           8
        .value_kind:     hidden_global_offset_y
      - .offset:         272
        .size:           8
        .value_kind:     hidden_global_offset_z
      - .offset:         280
        .size:           2
        .value_kind:     hidden_grid_dims
      - .offset:         304
        .size:           8
        .value_kind:     hidden_multigrid_sync_arg
      - .offset:         336
        .size:           4
        .value_kind:     hidden_dynamic_lds_size
    .group_segment_fixed_size: 0
    .kernarg_segment_align: 8
    .kernarg_segment_size: 472
    .language:       OpenCL C
    .language_version:
      - 2
      - 0
    .max_flat_workgroup_size: 512
    .name:           _Z10hybrid_fwd4Args
    .private_segment_fixed_size: 0
    .sgpr_count:     108
    .sgpr_spill_count: 71
    .symbol:         _Z10hybrid_fwd4Args.kd
    .uniform_work_group_size: 1
    .uses_dynamic_stack: false
    .vgpr_count:     256
    .vgpr_spill_count: 0
    .wavefront_size: 64
